# staggers: waves 4-7 delayed at the start of the weight-prep phase (s_sleep 24) and of every indexer score loop (s_sleep 20), plus the dsa_attn stagger
# baseline (speedup 1.0000x reference)
; __device__ __forceinline__ int fresh_tid() { int t = threadIdx.x; asm volatile("" : "+v"(t)); return t; }
; #define LAS __attribute__((address_space(3)))
; __device__ __forceinline__ void p0_weights(const Params& p, LAS unsigned char* lds) {
;     const int tid = fresh_tid(), lane = tid & 63, wave = tid >> 6, G = gridDim.x;
;     const int gw = blockIdx.x * NWAVE + wave, NGW = G * NWAVE;
;     unsigned char* ws = p.ws;
;     {
;         LAS float* scr = (LAS float*)(lds + wave * 16384);
;         for (int it = gw; it < 11904; it += NGW) {
;             const float* W; int K, N, nblk, mode = 0, r = it; bf16_t* WT;
;             if (r < 1536) { W = p.in[6]; K = 1024; N = 3072; nblk = 96; WT = (bf16_t*)(ws + WS_WQKV); }
;             else if ((r -= 1536) < 512) { W = p.in[7]; K = 1024; N = 1024; nblk = 32; WT = (bf16_t*)(ws + WS_WSBO); }
;             else if ((r -= 512) < 1408) { W = p.in[8]; K = 1024; N = DSA_N; nblk = 88; WT = (bf16_t*)(ws + WS_WDIN); }
;             else if ((r -= 1408) < 2816) { W = p.in[14]; K = 1024; N = FFN2; nblk = 176; WT = (bf16_t*)(ws + WS_WUP0); mode = 1; }
;             else if ((r -= 2816) < 2816) { W = p.in[14] + (size_t)DM * FFN2; K = 1024; N = FFN2; nblk = 176; WT = (bf16_t*)(ws + WS_WUP1); mode = 1; }
;             else if ((r -= 2816) < 1408) { W = p.in[17]; K = FFN; N = 1024; nblk = 32; WT = (bf16_t*)(ws + WS_WDN0); }
;             else { r -= 1408; W = p.in[17] + (size_t)FFN * DM; K = FFN; N = 1024; nblk = 32; WT = (bf16_t*)(ws + WS_WDN1); }
;             const int kb = r / nblk, nb = r % nblk, n0 = nb * 32;
;             int dst = n0;
;             if (mode == 1) { const int bj = n0 / FFN, f = n0 % FFN; dst = 256 * (f / 128) + 128 * bj + (f % 128); }
;             transpose_item(W, K, N, WT, dst, scr, kb * 64, n0, lane);
.LBB0_81:
	s_or_b64 exec, exec, s[4:5]
	s_mov_b64 s[14:15], s[82:83]
	s_waitcnt lgkmcnt(0)
	s_barrier
	v_readfirstlane_b32 s32, v194
	s_lshr_b32 s32, s32, 6
	s_cmp_lt_u32 s32, 4
	s_cbranch_scc1 .Lstag_p1
	s_sleep 24
.Lstag_p1:
	s_load_dwordx2 s[12:13], s[14:15], 0x98
	s_load_dwordx4 s[4:7], s[14:15], 0x58
	v_mov_b32_e32 v0, v194
	s_lshl_b32 s66, s76, 3
	v_ashrrev_i32_e32 v18, 6, v0
	v_add_u32_e32 v35, s66, v18
	s_movk_i32 s0, 0x2e80
	v_and_b32_e32 v34, 63, v0
	s_lshl_b32 s97, s72, 3
	v_cmp_gt_i32_e32 vcc, s0, v35
	s_and_saveexec_b64 s[16:17], vcc
	s_cbranch_execz .LBB0_116
	s_waitcnt lgkmcnt(0)
	s_add_u32 s24, s12, 0x3000000
	s_addc_u32 s25, s13, 0
	s_add_u32 s26, s12, 0x2a00000
	s_addc_u32 s27, s13, 0
	s_add_u32 s28, s12, 0x1f00000
	s_addc_u32 s29, s13, 0
	s_add_u32 s30, s12, 0x1400000
	s_addc_u32 s31, s13, 0
	s_add_u32 s34, s12, 0xa00000
	s_load_dwordx4 s[8:11], s[14:15], 0x30
	s_load_dwordx2 s[18:19], s[14:15], 0x40
	s_load_dwordx2 s[20:21], s[14:15], 0x70
	s_load_dwordx2 s[22:23], s[14:15], 0x88
	s_addc_u32 s35, s13, 0
	s_add_u32 s36, s12, 0x800000
	s_addc_u32 s37, s13, 0
	s_add_u32 s38, s12, 0x200000
	s_addc_u32 s39, s13, 0
	s_waitcnt lgkmcnt(0)
	s_add_u32 s40, s22, 0xb00000
	v_lshl_add_u32 v1, v18, 14, 0
	v_and_b32_e32 v2, 7, v0
	v_lshrrev_b32_e32 v20, 3, v34
	s_addc_u32 s41, s23, 0
	v_lshlrev_b32_e32 v19, 2, v2
	v_lshl_add_u32 v3, v2, 4, v1
	v_mul_u32_u24_e32 v4, 0x84, v20
	v_lshlrev_b32_e32 v0, 3, v2
	v_mul_u32_u24_e32 v2, 0x420, v2
	v_lshlrev_b32_e32 v5, 2, v20
	s_add_u32 s42, s20, 0x1600000
	v_or_b32_e32 v21, 8, v20
	v_or_b32_e32 v22, 16, v20
	v_or_b32_e32 v23, 24, v20
	v_or_b32_e32 v24, 32, v20
	v_or_b32_e32 v25, 40, v20
	v_or_b32_e32 v26, 48, v20
	v_or_b32_e32 v27, 56, v20
	v_mov_b32_e32 v9, 0
	v_add3_u32 v28, v1, v2, v5
	s_addc_u32 s43, s21, 0
	s_mov_b64 s[46:47], 0
	s_movk_i32 s0, 0x5ff
	s_movk_i32 s1, 0x7ff
	s_movk_i32 s2, 0xd7f
	s_movk_i32 s33, 0x187f
	s_movk_i32 s44, 0x237f
	s_movk_i32 s45, 0x28ff
	v_lshlrev_b32_e32 v8, 1, v0
	s_movk_i32 s60, 0x7fff
	s_mov_b32 s61, 0xffff0000
	s_movk_i32 s62, 0x2e7f
	v_mov_b32_e32 v29, 8
	v_mov_b32_e32 v30, 7
	v_add_u32_e32 v31, v3, v4
	v_mov_b32_e32 v32, v35
	s_branch .LBB0_84

; __device__ __forceinline__ void indexer_phase(const bf16_t* PJ, float* rk, unsigned short* SEL, LAS unsigned char* lds) {
;     ...
;         const int b = gl >> 9, jj = gl & 511, t0 = (jj < 256 ? jj : 767 - jj) * 8;
;         const size_t rowbase = (size_t)b * SEQ;
;         const int t = t0 + wid;
;         unsigned short* selrow = SEL + (rowbase + t) * 256;
;         if (t0 + 7 < 256) {
; #pragma unroll
;             for (int i = 0; i < 4; ++i) { const int s = lane + 64 * i; selrow[s] = (unsigned short)(s <= t ? s : 0); }
;             continue;
;         }
;         {
;             const int g = r32 >> 3, hp = (r32 >> 2) & 1, ii = r32 & 3, tq = 2 * hp + (g >> 1), head = 4 * (g & 1) + ii;
;             bf16x8 af[2][4]; float wq[2][2][8];
; #pragma unroll
;             for (int rt = 0; rt < 2; ++rt) {
;                 const bf16_t* qp = PJ + (rowbase + t0 + 4 * rt + tq) * PROJ_LD + PJ_QI + head * 64 + hi * 8;
; #pragma unroll
;                 for (int kk = 0; kk < 4; ++kk) af[rt][kk] = *(const bf16x8*)(qp + kk * 16);
; #pragma unroll
;                 for (int qq = 0; qq < 2; ++qq) { const u32x4 w = *(const u32x4*)(PJ + (rowbase + t0 + 4 * rt + 2 * hi + qq) * PROJ_LD + PJ_WI);
;                     const float sc = 0.35355339059327373f;
;                     wq[rt][qq][0] = bflo(w.x) * sc; wq[rt][qq][1] = bfhi(w.x) * sc; wq[rt][qq][2] = bflo(w.y) * sc; wq[rt][qq][3] = bfhi(w.y) * sc;
;                     wq[rt][qq][4] = bflo(w.z) * sc; wq[rt][qq][5] = bfhi(w.z) * sc; wq[rt][qq][6] = bflo(w.w) * sc; wq[rt][qq][7] = bfhi(w.w) * sc; }
;             }
;             float rmax[2][2], rmin[2][2];
; #pragma unroll
;             for (int rt = 0; rt < 2; ++rt)
; #pragma unroll
;                 for (int qq = 0; qq < 2; ++qq) { rmax[rt][qq] = -INFINITY; rmin[rt][qq] = INFINITY; }
;             const int nkt = (t0 + 8 + 31) >> 5;
;             const bf16_t* kbase = PJ + (rowbase + r32) * PROJ_LD + PJ_KI + hi * 8;
;             bf16x8 bcur[4], bnxt[4];
;             int kt = wid;
; #pragma unroll
;             for (int kk = 0; kk < 4; ++kk) bcur[kk] = *(const bf16x8*)(kbase + (size_t)(32 * kt) * PROJ_LD + kk * 16);
.LBB0_864:
	s_and_b32 s0, s2, 0x1ff
	s_ashr_i32 s24, s2, 9
	s_sub_i32 s1, 0x2ff, s0
	s_cmpk_lt_u32 s0, 0x100
	s_cselect_b32 s0, s0, s1
	s_lshl_b32 s1, s0, 3
	s_ashr_i32 s25, s24, 31
	s_add_i32 s77, s1, s33
	s_lshl_b64 s[26:27], s[24:25], 12
	s_ashr_i32 s3, s77, 31
	s_add_u32 s24, s26, s77
	s_addc_u32 s25, s27, s3
	s_lshl_b64 s[24:25], s[24:25], 9
	s_add_u32 s60, s4, s24
	s_addc_u32 s61, s5, s25
	s_cmp_gt_u32 s0, 31
	s_mov_b64 s[24:25], -1
	s_cbranch_scc0 .LBB0_1027
	s_add_i32 s0, s1, 39
	s_lshr_b32 s0, s0, 5
	s_cmp_ge_i32 s33, s0
	s_cbranch_scc1 .LBB0_873
	v_readlane_b32 s24, v255, 13
	s_add_u32 s3, s26, s1
	v_readlane_b32 s25, v255, 14
	v_or_b32_e32 v0, s3, v112
	s_addc_u32 s6, s27, 0
	v_mov_b64_e32 v[16:17], s[24:25]
	v_mad_u64_u32 v[0:1], s[24:25], v0, s7, v[16:17]
	v_mad_i32_i24 v1, s6, v177, v1
	v_lshl_add_u64 v[0:1], v[0:1], 0, v[114:115]
	v_mov_b32_e32 v123, v115
	v_lshl_add_u64 v[18:19], v[0:1], 0, v[122:123]
	v_or_b32_e32 v0, s3, v116
	v_add_co_u32_e32 v20, vcc, s44, v18
	v_mad_u64_u32 v[0:1], s[24:25], v0, s7, v[16:17]
	v_mad_i32_i24 v1, s6, v177, v1
	s_mov_b64 s[24:25], vcc
	v_add_co_u32_e32 v0, vcc, s44, v0
	v_or_b32_e32 v4, s3, v120
	s_nop 0
	v_addc_co_u32_e32 v1, vcc, 0, v1, vcc
	v_mad_u64_u32 v[4:5], s[28:29], v4, s7, v[16:17]
	s_or_b32 s3, s3, 4
	v_mad_i32_i24 v5, s6, v177, v5
	v_add_co_u32_e32 v4, vcc, s44, v4
	v_or_b32_e32 v8, s3, v116
	s_nop 0
	v_addc_co_u32_e32 v5, vcc, 0, v5, vcc
	v_mad_u64_u32 v[8:9], s[28:29], v8, s7, v[16:17]
	v_mad_i32_i24 v9, s6, v177, v9
	v_add_co_u32_e32 v8, vcc, s44, v8
	v_or_b32_e32 v12, s3, v120
	s_nop 0
	v_addc_co_u32_e32 v9, vcc, 0, v9, vcc
	s_mov_b64 s[30:31], 0x1100
	s_waitcnt lgkmcnt(0)
	v_mad_u64_u32 v[12:13], s[28:29], v12, s7, v[16:17]
	v_lshl_add_u64 v[22:23], v[18:19], 0, s[30:31]
	v_mad_i32_i24 v13, s6, v177, v13
	v_add_co_u32_e32 v12, vcc, s44, v12
	v_or_b32_e32 v18, s3, v112
	global_load_dwordx4 v[0:3], v[0:1], off offset:1408
	v_addc_co_u32_e32 v13, vcc, 0, v13, vcc
	v_addc_co_u32_e64 v21, vcc, 0, v19, s[24:25]
	v_mad_u64_u32 v[18:19], s[24:25], v18, s7, v[16:17]
	v_mad_i32_i24 v19, s6, v177, v19
	global_load_dwordx4 v[4:7], v[4:5], off offset:1408
	v_lshl_add_u64 v[18:19], v[18:19], 0, v[114:115]
	v_lshl_add_u64 v[18:19], v[18:19], 0, v[122:123]
	global_load_dwordx4 v[8:11], v[8:9], off offset:1408
	v_or_b32_e32 v190, s1, v116
	global_load_dwordx4 v[12:15], v[12:13], off offset:1408
	s_nop 0
	global_load_dwordx4 v[64:67], v[22:23], off offset:32
	global_load_dwordx4 v[68:71], v[22:23], off offset:64
	global_load_dwordx4 v[72:75], v[20:21], off offset:256
	global_load_dwordx4 v[76:79], v[22:23], off offset:96
	v_lshl_add_u64 v[20:21], v[18:19], 0, s[30:31]
	v_add_co_u32_e32 v22, vcc, s44, v18
	v_or_b32_e32 v18, s26, v110
	v_mad_u64_u32 v[16:17], s[24:25], v18, s7, v[16:17]
	v_mad_i32_i24 v17, s27, v177, v17
	v_lshl_add_u64 v[16:17], v[16:17], 0, v[122:123]
	s_mov_b64 s[24:25], 0x1500
	v_lshl_add_u64 v[124:125], v[16:17], 0, s[24:25]
	v_lshl_add_u64 v[216:217], v[218:219], 0, v[124:125]
	v_readlane_b32 s24, v255, 21
	v_readlane_b32 s25, v255, 22
	v_addc_co_u32_e32 v23, vcc, 0, v19, vcc
	s_nop 0
	v_lshl_add_u64 v[16:17], v[124:125], 0, s[24:25]
	global_load_dwordx4 v[80:83], v[20:21], off offset:32
	global_load_dwordx4 v[84:87], v[20:21], off offset:64
	global_load_dwordx4 v[96:99], v[16:17], off offset:96
	global_load_dwordx4 v[100:103], v[16:17], off offset:64
	global_load_dwordx4 v[104:107], v[16:17], off offset:32
	s_nop 0
	global_load_dwordx4 v[244:247], v[16:17], off
	s_nop 0
	global_load_dwordx4 v[88:91], v[22:23], off offset:256
	global_load_dwordx4 v[92:95], v[20:21], off offset:96
	v_mov_b64_e32 v[54:55], v[34:35]
	v_mov_b64_e32 v[58:59], v[38:39]
	v_mov_b64_e32 v[62:63], v[42:43]
	v_mov_b64_e32 v[50:51], v[46:47]
	v_or_b32_e32 v191, 1, v190
	v_or_b32_e32 v192, 4, v190
	v_or_b32_e32 v193, 5, v190
	v_mov_b32_e32 v189, 0xff800000
	v_mov_b32_e32 v188, 0x7f800000
	v_mov_b32_e32 v196, v171
	v_readlane_b32 s6, v255, 20
	v_mov_b64_e32 v[52:53], v[32:33]
	v_mov_b64_e32 v[56:57], v[36:37]
	v_mov_b64_e32 v[60:61], v[40:41]
	v_mov_b64_e32 v[48:49], v[44:45]
	v_mov_b32_e32 v186, 0x7f800000
	v_mov_b32_e32 v184, 0x7f800000
	v_mov_b32_e32 v123, 0x7f800000
	v_mov_b32_e32 v187, 0xff800000
	v_mov_b32_e32 v185, 0xff800000
	v_mov_b32_e32 v183, 0xff800000
	s_mov_b32 s1, s33
	s_waitcnt vmcnt(15)
	v_and_b32_e32 v20, 0xffff0000, v0
	v_lshlrev_b32_e32 v21, 16, v0
	v_and_b32_e32 v0, 0xffff0000, v1
	v_lshlrev_b32_e32 v1, 16, v1
	v_pk_mul_f32 v[128:129], v[0:1], s[58:59] op_sel_hi:[1,0]
	v_and_b32_e32 v0, 0xffff0000, v3
	v_lshlrev_b32_e32 v1, 16, v3
	v_pk_mul_f32 v[132:133], v[0:1], s[58:59] op_sel_hi:[1,0]
	s_waitcnt vmcnt(14)
	v_and_b32_e32 v0, 0xffff0000, v4
	v_lshlrev_b32_e32 v1, 16, v4
	v_pk_mul_f32 v[134:135], v[0:1], s[58:59] op_sel_hi:[1,0]
	v_and_b32_e32 v0, 0xffff0000, v5
	v_lshlrev_b32_e32 v1, 16, v5
	v_pk_mul_f32 v[136:137], v[0:1], s[58:59] op_sel_hi:[1,0]
	v_and_b32_e32 v0, 0xffff0000, v6
	v_lshlrev_b32_e32 v1, 16, v6
	v_pk_mul_f32 v[138:139], v[0:1], s[58:59] op_sel_hi:[1,0]
	v_and_b32_e32 v0, 0xffff0000, v7
	v_lshlrev_b32_e32 v1, 16, v7
	v_pk_mul_f32 v[140:141], v[0:1], s[58:59] op_sel_hi:[1,0]
	s_waitcnt vmcnt(13)
	v_and_b32_e32 v0, 0xffff0000, v8
	v_lshlrev_b32_e32 v1, 16, v8
	v_pk_mul_f32 v[142:143], v[0:1], s[58:59] op_sel_hi:[1,0]
	v_and_b32_e32 v0, 0xffff0000, v9
	v_lshlrev_b32_e32 v1, 16, v9
	v_pk_mul_f32 v[144:145], v[0:1], s[58:59] op_sel_hi:[1,0]
	v_and_b32_e32 v0, 0xffff0000, v10
	v_lshlrev_b32_e32 v1, 16, v10
	v_pk_mul_f32 v[146:147], v[0:1], s[58:59] op_sel_hi:[1,0]
	v_and_b32_e32 v0, 0xffff0000, v11
	v_lshlrev_b32_e32 v1, 16, v11
	v_pk_mul_f32 v[148:149], v[0:1], s[58:59] op_sel_hi:[1,0]
	s_waitcnt vmcnt(12)
	v_and_b32_e32 v0, 0xffff0000, v12
	v_lshlrev_b32_e32 v1, 16, v12
	v_pk_mul_f32 v[150:151], v[0:1], s[58:59] op_sel_hi:[1,0]
	v_and_b32_e32 v0, 0xffff0000, v13
	v_lshlrev_b32_e32 v1, 16, v13
	v_pk_mul_f32 v[152:153], v[0:1], s[58:59] op_sel_hi:[1,0]
	v_and_b32_e32 v0, 0xffff0000, v14
	v_lshlrev_b32_e32 v1, 16, v14
	v_and_b32_e32 v22, 0xffff0000, v2
	v_lshlrev_b32_e32 v23, 16, v2
	v_pk_mul_f32 v[154:155], v[0:1], s[58:59] op_sel_hi:[1,0]
	v_and_b32_e32 v0, 0xffff0000, v15
	v_lshlrev_b32_e32 v1, 16, v15
	v_pk_mul_f32 v[126:127], v[20:21], s[58:59] op_sel_hi:[1,0]
	v_pk_mul_f32 v[130:131], v[22:23], s[58:59] op_sel_hi:[1,0]
	v_pk_mul_f32 v[156:157], v[0:1], s[58:59] op_sel_hi:[1,0]
	s_waitcnt vmcnt(0)
	s_cmp_lt_u32 s33, 4
	s_cbranch_scc1 .Lidx_nostag
	s_sleep 20
.Lidx_nostag:
	s_add_i32 s32, s1, 8
	s_cmp_lt_i32 s32, s0
	s_cbranch_scc0 .Lidx_loopA
	s_add_i32 s32, s6, 0x100
	v_mad_i64_i32 v[0:1], s[26:27], s32, v177, v[216:217]
	s_add_i32 s32, s32, 16
	v_mad_i64_i32 v[220:221], s[26:27], s32, v177, v[216:217]
	global_load_dwordx4 v[52:55], v[0:1], off
	global_load_dwordx4 v[56:59], v[220:221], off
	global_load_dwordx4 v[60:63], v[0:1], off offset:64
	global_load_dwordx4 v[48:51], v[220:221], off offset:64
